# SSD conv+silu rewritten with up-front row reads and FMA chains; decay-weight LDS reads hoisted; weight-prep scale loads and group-norm row loop de-serialised
# speedup vs baseline: 1.0593x; 1.0202x over previous
; __device__ __forceinline__ int ltid() { int t = threadIdx.x; asm volatile("" : "+v"(t)); return t; }
; __device__ __forceinline__ int lbid() { int t = blockIdx.x; asm volatile("" : "+s"(t)); return t; }
; __device__ __forceinline__ int lgdim() { int t = gridDim.x; asm volatile("" : "+s"(t)); return t; }
; __device__ __forceinline__ unsigned pk2(float lo, float hi) { unsigned r; asm volatile("v_cvt_pk_bf16_f32 %0, %1, %2" : "=v"(r) : "v"(lo), "v"(hi)); return r; }
; __device__ __forceinline__ float lo_f(unsigned w) { return __uint_as_float(w << 16); }
; __device__ __forceinline__ float hi_f(unsigned w) { return __uint_as_float(w & 0xffff0000u); }
; __device__ __forceinline__ void ssd_norm_rows(CPar p) {
;     const int lane = ltid() & 63, gw = lbid() * 8 + (ltid() >> 6), ngw = lgdim() * 8;
;     bf16_t* Z = (bf16_t*)(p->ws + WS_Z);
;     for (int r = gw; r < NROWS; r += ngw) {
; #pragma unroll
;         for (int j = 0; j < 2; ++j) { u32x4* zp = (u32x4*)(Z + (size_t)r * 1024 + j * 512 + lane * 8); const u32x4 w = *zp;
;             float f[8] = {lo_f(w[0]), hi_f(w[0]), lo_f(w[1]), hi_f(w[1]), lo_f(w[2]), hi_f(w[2]), lo_f(w[3]), hi_f(w[3])};
;             float ss = 0.f;
; #pragma unroll
;             for (int i = 0; i < 8; ++i) ss += f[i] * f[i];
;             const float rs = rsqrtf(wave_sum(ss) * (1.f / 512.f) + EPS);
;             u32x4 o; o[0] = pk2(f[0] * rs, f[1] * rs); o[1] = pk2(f[2] * rs, f[3] * rs); o[2] = pk2(f[4] * rs, f[5] * rs); o[3] = pk2(f[6] * rs, f[7] * rs); *zp = o; }
;     }
; }
.LBB0_224:
	s_andn2_b64 vcc, exec, s[18:19]
	s_cbranch_vccnz .LBB0_8
	v_readlane_b32 s0, v255, 30
	v_readlane_b32 s1, v255, 31
	s_load_dwordx2 s[0:1], s[0:1], 0x118
	s_mov_b64 s[18:19], -1
	s_waitcnt lgkmcnt(0)
	s_add_u32 s0, s0, 0x1d1c1000
	s_addc_u32 s1, s1, 0
	v_writelane_b32 v255, s0, 49
	s_nop 1
	v_writelane_b32 v255, s1, 50
	s_nop 0
	v_readlane_b32 s0, v255, 48
	s_cmp_lt_i32 s0, 2
	s_cbranch_scc1 .LBB0_778
	v_readlane_b32 s0, v255, 48
	s_cmp_gt_i32 s0, 2
	s_cbranch_scc0 .LBB0_243
	s_waitcnt vmcnt(0)
	v_mov_b32_e32 v4, v200
	v_readlane_b32 s0, v254, 0
	v_mov_b32_e32 v1, v200
	s_mov_b32 s1, 0x10600
	v_ashrrev_i32_e32 v1, 6, v1
	v_lshl_add_u32 v2, s0, 3, v1
	s_mov_b32 s0, s68
	v_cmp_gt_i32_e32 vcc, s1, v2
	s_and_saveexec_b64 s[18:19], vcc
	s_cbranch_execz .LBB0_230
	v_and_b32_e32 v1, 64, v205
	v_add_u32_e32 v3, 64, v1
	v_xor_b32_e32 v1, 1, v205
	v_cmp_lt_i32_e32 vcc, v1, v3
	v_xor_b32_e32 v5, 2, v205
	s_lshl_b32 s24, s0, 3
	v_cndmask_b32_e32 v1, v205, v1, vcc
	v_cmp_lt_i32_e32 vcc, v5, v3
	v_readlane_b32 s0, v255, 30
	v_readlane_b32 s1, v255, 31
	v_cndmask_b32_e32 v5, v205, v5, vcc
	v_lshlrev_b32_e32 v6, 2, v5
	v_xor_b32_e32 v5, 4, v205
	v_cmp_lt_i32_e32 vcc, v5, v3
	s_load_dwordx2 s[0:1], s[0:1], 0x118
	s_ashr_i32 s25, s24, 31
	v_cndmask_b32_e32 v5, v205, v5, vcc
	v_lshlrev_b32_e32 v7, 2, v5
	v_xor_b32_e32 v5, 8, v205
	v_cmp_lt_i32_e32 vcc, v5, v3
	v_lshlrev_b32_e32 v1, 2, v1
	s_lshl_b64 s[26:27], s[24:25], 11
	v_cndmask_b32_e32 v5, v205, v5, vcc
	v_lshlrev_b32_e32 v8, 2, v5
	v_xor_b32_e32 v5, 16, v205
	v_cmp_lt_i32_e32 vcc, v5, v3
	s_mov_b64 s[28:29], 0
	s_nop 0
	v_cndmask_b32_e32 v5, v205, v5, vcc
	v_lshlrev_b32_e32 v9, 2, v5
	v_xor_b32_e32 v5, 32, v205
	v_cmp_lt_i32_e32 vcc, v5, v3
	s_nop 1
	v_cndmask_b32_e32 v3, v205, v5, vcc
	v_lshlrev_b32_e32 v10, 2, v3
	v_ashrrev_i32_e32 v3, 31, v2
	v_lshlrev_b64 v[12:13], 11, v[2:3]
	v_and_b32_e32 v3, 63, v4
	v_lshl_or_b32 v12, v3, 4, v12
	s_waitcnt lgkmcnt(0)
	v_lshl_add_u64 v[4:5], s[0:1], 0, v[12:13]
	s_mov_b64 s[0:1], 0xab01400
	v_lshl_add_u64 v[4:5], v[4:5], 0, s[0:1]
	global_load_dwordx4 v[72:75], v[4:5], off offset:-1024
	global_load_dwordx4 v[76:79], v[4:5], off
	s_waitcnt vmcnt(0)
.LBB0_229:
	v_add_u32_e32 v2, s24, v2
	v_lshl_add_u64 v[88:89], v[4:5], 0, s[26:27]
	global_load_dwordx4 v[80:83], v[88:89], off offset:-1024
	global_load_dwordx4 v[84:87], v[88:89], off
	s_waitcnt vmcnt(4)
	v_lshlrev_b32_e32 v90, 16, v72
	v_and_b32_e32 v91, 0xffff0000, v72
	v_lshlrev_b32_e32 v98, 16, v76
	v_and_b32_e32 v99, 0xffff0000, v76
	v_lshlrev_b32_e32 v92, 16, v73
	v_and_b32_e32 v93, 0xffff0000, v73
	v_lshlrev_b32_e32 v100, 16, v77
	v_and_b32_e32 v101, 0xffff0000, v77
	v_lshlrev_b32_e32 v94, 16, v74
	v_and_b32_e32 v95, 0xffff0000, v74
	v_lshlrev_b32_e32 v102, 16, v78
	v_and_b32_e32 v103, 0xffff0000, v78
	v_lshlrev_b32_e32 v96, 16, v75
	v_and_b32_e32 v97, 0xffff0000, v75
	v_lshlrev_b32_e32 v104, 16, v79
	v_and_b32_e32 v105, 0xffff0000, v79
	v_mul_f32_e32 v106, v90, v90
	v_mul_f32_e32 v107, v98, v98
	v_fmac_f32_e32 v106, v91, v91
	v_fmac_f32_e32 v107, v99, v99
	v_fmac_f32_e32 v106, v92, v92
	v_fmac_f32_e32 v107, v100, v100
	v_fmac_f32_e32 v106, v93, v93
	v_fmac_f32_e32 v107, v101, v101
	v_fmac_f32_e32 v106, v94, v94
	v_fmac_f32_e32 v107, v102, v102
	v_fmac_f32_e32 v106, v95, v95
	v_fmac_f32_e32 v107, v103, v103
	v_fmac_f32_e32 v106, v96, v96
	v_fmac_f32_e32 v107, v104, v104
	v_fmac_f32_e32 v106, v97, v97
	v_fmac_f32_e32 v107, v105, v105
	ds_bpermute_b32 v108, v1, v106
	ds_bpermute_b32 v109, v1, v107
	s_waitcnt lgkmcnt(0)
	v_add_f32_e32 v106, v106, v108
	v_add_f32_e32 v107, v107, v109
	ds_bpermute_b32 v108, v6, v106
	ds_bpermute_b32 v109, v6, v107
	s_waitcnt lgkmcnt(0)
	v_add_f32_e32 v106, v106, v108
	v_add_f32_e32 v107, v107, v109
	ds_bpermute_b32 v108, v7, v106
	ds_bpermute_b32 v109, v7, v107
	s_waitcnt lgkmcnt(0)
	v_add_f32_e32 v106, v106, v108
	v_add_f32_e32 v107, v107, v109
	ds_bpermute_b32 v108, v8, v106
	ds_bpermute_b32 v109, v8, v107
	s_waitcnt lgkmcnt(0)
	v_add_f32_e32 v106, v106, v108
	v_add_f32_e32 v107, v107, v109
	ds_bpermute_b32 v108, v9, v106
	ds_bpermute_b32 v109, v9, v107
	s_waitcnt lgkmcnt(0)
	v_add_f32_e32 v106, v106, v108
	v_add_f32_e32 v107, v107, v109
	ds_bpermute_b32 v108, v10, v106
	ds_bpermute_b32 v109, v10, v107
	s_waitcnt lgkmcnt(0)
	v_add_f32_e32 v106, v106, v108
	v_add_f32_e32 v107, v107, v109
	v_fmamk_f32 v106, v106, 0x3b000000, v202
	v_cmp_gt_f32_e32 vcc, s38, v106
	v_mul_f32_e32 v110, 0x4b800000, v106
	s_nop 0
	v_cndmask_b32_e32 v106, v106, v110, vcc
	v_rsq_f32_e32 v106, v106
	s_nop 0
	v_mul_f32_e32 v110, 0x45800000, v106
	v_cndmask_b32_e32 v106, v106, v110, vcc
	v_fmamk_f32 v107, v107, 0x3b000000, v202
	v_cmp_gt_f32_e32 vcc, s38, v107
	v_mul_f32_e32 v111, 0x4b800000, v107
	s_nop 0
	v_cndmask_b32_e32 v107, v107, v111, vcc
	v_rsq_f32_e32 v107, v107
	s_nop 0
	v_mul_f32_e32 v111, 0x45800000, v107
	v_cndmask_b32_e32 v107, v107, v111, vcc
	v_mul_f32_e32 v90, v106, v90
	v_mul_f32_e32 v91, v106, v91
	v_cvt_pk_bf16_f32 v72, v90, v91
	v_mul_f32_e32 v98, v107, v98
	v_mul_f32_e32 v99, v107, v99
	v_cvt_pk_bf16_f32 v76, v98, v99
	v_mul_f32_e32 v92, v106, v92
	v_mul_f32_e32 v93, v106, v93
	v_cvt_pk_bf16_f32 v73, v92, v93
	v_mul_f32_e32 v100, v107, v100
	v_mul_f32_e32 v101, v107, v101
	v_cvt_pk_bf16_f32 v77, v100, v101
	v_mul_f32_e32 v94, v106, v94
	v_mul_f32_e32 v95, v106, v95
	v_cvt_pk_bf16_f32 v74, v94, v95
	v_mul_f32_e32 v102, v107, v102
	v_mul_f32_e32 v103, v107, v103
	v_cvt_pk_bf16_f32 v78, v102, v103
	v_mul_f32_e32 v96, v106, v96
	v_mul_f32_e32 v97, v106, v97
	v_cvt_pk_bf16_f32 v75, v96, v97
	v_mul_f32_e32 v104, v107, v104
	v_mul_f32_e32 v105, v107, v105
	v_cvt_pk_bf16_f32 v79, v104, v105
	global_store_dwordx4 v[4:5], v[72:75], off offset:-1024
	global_store_dwordx4 v[4:5], v[76:79], off
	v_cmp_lt_i32_e32 vcc, s73, v2
	v_lshl_add_u64 v[4:5], v[4:5], 0, s[26:27]
	s_or_b64 s[28:29], vcc, s[28:29]
	s_andn2_b64 exec, exec, s[28:29]
	s_cbranch_execz .LBB0_230
; __device__ __forceinline__ int ltid() { int t = threadIdx.x; asm volatile("" : "+v"(t)); return t; }
; __device__ __forceinline__ int lbid() { int t = blockIdx.x; asm volatile("" : "+s"(t)); return t; }
; __device__ __forceinline__ int lgdim() { int t = gridDim.x; asm volatile("" : "+s"(t)); return t; }
; __device__ __forceinline__ unsigned pk2(float lo, float hi) { unsigned r; asm volatile("v_cvt_pk_bf16_f32 %0, %1, %2" : "=v"(r) : "v"(lo), "v"(hi)); return r; }
; __device__ __forceinline__ float lo_f(unsigned w) { return __uint_as_float(w << 16); }
; __device__ __forceinline__ float hi_f(unsigned w) { return __uint_as_float(w & 0xffff0000u); }
; __device__ __forceinline__ void ssd_norm_rows(CPar p) {
;     const int lane = ltid() & 63, gw = lbid() * 8 + (ltid() >> 6), ngw = lgdim() * 8;
;     bf16_t* Z = (bf16_t*)(p->ws + WS_Z);
;     for (int r = gw; r < NROWS; r += ngw) {
; #pragma unroll
;         for (int j = 0; j < 2; ++j) { u32x4* zp = (u32x4*)(Z + (size_t)r * 1024 + j * 512 + lane * 8); const u32x4 w = *zp;
;             float f[8] = {lo_f(w[0]), hi_f(w[0]), lo_f(w[1]), hi_f(w[1]), lo_f(w[2]), hi_f(w[2]), lo_f(w[3]), hi_f(w[3])};
;             float ss = 0.f;
; #pragma unroll
;             for (int i = 0; i < 8; ++i) ss += f[i] * f[i];
;             const float rs = rsqrtf(wave_sum(ss) * (1.f / 512.f) + EPS);
;             u32x4 o; o[0] = pk2(f[0] * rs, f[1] * rs); o[1] = pk2(f[2] * rs, f[3] * rs); o[2] = pk2(f[4] * rs, f[5] * rs); o[3] = pk2(f[6] * rs, f[7] * rs); *zp = o; }
;     }
; }
	v_add_u32_e32 v2, s24, v2
	v_lshl_add_u64 v[88:89], v[4:5], 0, s[26:27]
	global_load_dwordx4 v[72:75], v[88:89], off offset:-1024
	global_load_dwordx4 v[76:79], v[88:89], off
	s_waitcnt vmcnt(4)
	v_lshlrev_b32_e32 v90, 16, v80
	v_and_b32_e32 v91, 0xffff0000, v80
	v_lshlrev_b32_e32 v98, 16, v84
	v_and_b32_e32 v99, 0xffff0000, v84
	v_lshlrev_b32_e32 v92, 16, v81
	v_and_b32_e32 v93, 0xffff0000, v81
	v_lshlrev_b32_e32 v100, 16, v85
	v_and_b32_e32 v101, 0xffff0000, v85
	v_lshlrev_b32_e32 v94, 16, v82
	v_and_b32_e32 v95, 0xffff0000, v82
	v_lshlrev_b32_e32 v102, 16, v86
	v_and_b32_e32 v103, 0xffff0000, v86
	v_lshlrev_b32_e32 v96, 16, v83
	v_and_b32_e32 v97, 0xffff0000, v83
	v_lshlrev_b32_e32 v104, 16, v87
	v_and_b32_e32 v105, 0xffff0000, v87
	v_mul_f32_e32 v106, v90, v90
	v_mul_f32_e32 v107, v98, v98
	v_fmac_f32_e32 v106, v91, v91
	v_fmac_f32_e32 v107, v99, v99
	v_fmac_f32_e32 v106, v92, v92
	v_fmac_f32_e32 v107, v100, v100
	v_fmac_f32_e32 v106, v93, v93
	v_fmac_f32_e32 v107, v101, v101
	v_fmac_f32_e32 v106, v94, v94
	v_fmac_f32_e32 v107, v102, v102
	v_fmac_f32_e32 v106, v95, v95
	v_fmac_f32_e32 v107, v103, v103
	v_fmac_f32_e32 v106, v96, v96
	v_fmac_f32_e32 v107, v104, v104
	v_fmac_f32_e32 v106, v97, v97
	v_fmac_f32_e32 v107, v105, v105
	ds_bpermute_b32 v108, v1, v106
	ds_bpermute_b32 v109, v1, v107
	s_waitcnt lgkmcnt(0)
	v_add_f32_e32 v106, v106, v108
	v_add_f32_e32 v107, v107, v109
	ds_bpermute_b32 v108, v6, v106
	ds_bpermute_b32 v109, v6, v107
	s_waitcnt lgkmcnt(0)
	v_add_f32_e32 v106, v106, v108
	v_add_f32_e32 v107, v107, v109
	ds_bpermute_b32 v108, v7, v106
	ds_bpermute_b32 v109, v7, v107
	s_waitcnt lgkmcnt(0)
	v_add_f32_e32 v106, v106, v108
	v_add_f32_e32 v107, v107, v109
	ds_bpermute_b32 v108, v8, v106
	ds_bpermute_b32 v109, v8, v107
	s_waitcnt lgkmcnt(0)
	v_add_f32_e32 v106, v106, v108
	v_add_f32_e32 v107, v107, v109
	ds_bpermute_b32 v108, v9, v106
	ds_bpermute_b32 v109, v9, v107
	s_waitcnt lgkmcnt(0)
	v_add_f32_e32 v106, v106, v108
	v_add_f32_e32 v107, v107, v109
	ds_bpermute_b32 v108, v10, v106
	ds_bpermute_b32 v109, v10, v107
	s_waitcnt lgkmcnt(0)
	v_add_f32_e32 v106, v106, v108
	v_add_f32_e32 v107, v107, v109
	v_fmamk_f32 v106, v106, 0x3b000000, v202
	v_cmp_gt_f32_e32 vcc, s38, v106
	v_mul_f32_e32 v110, 0x4b800000, v106
	s_nop 0
	v_cndmask_b32_e32 v106, v106, v110, vcc
	v_rsq_f32_e32 v106, v106
	s_nop 0
	v_mul_f32_e32 v110, 0x45800000, v106
	v_cndmask_b32_e32 v106, v106, v110, vcc
	v_fmamk_f32 v107, v107, 0x3b000000, v202
	v_cmp_gt_f32_e32 vcc, s38, v107
	v_mul_f32_e32 v111, 0x4b800000, v107
	s_nop 0
	v_cndmask_b32_e32 v107, v107, v111, vcc
	v_rsq_f32_e32 v107, v107
	s_nop 0
	v_mul_f32_e32 v111, 0x45800000, v107
	v_cndmask_b32_e32 v107, v107, v111, vcc
	v_mul_f32_e32 v90, v106, v90
	v_mul_f32_e32 v91, v106, v91
	v_cvt_pk_bf16_f32 v80, v90, v91
	v_mul_f32_e32 v98, v107, v98
	v_mul_f32_e32 v99, v107, v99
	v_cvt_pk_bf16_f32 v84, v98, v99
	v_mul_f32_e32 v92, v106, v92
	v_mul_f32_e32 v93, v106, v93
	v_cvt_pk_bf16_f32 v81, v92, v93
	v_mul_f32_e32 v100, v107, v100
	v_mul_f32_e32 v101, v107, v101
	v_cvt_pk_bf16_f32 v85, v100, v101
	v_mul_f32_e32 v94, v106, v94
	v_mul_f32_e32 v95, v106, v95
	v_cvt_pk_bf16_f32 v82, v94, v95
	v_mul_f32_e32 v102, v107, v102
	v_mul_f32_e32 v103, v107, v103
	v_cvt_pk_bf16_f32 v86, v102, v103
	v_mul_f32_e32 v96, v106, v96
	v_mul_f32_e32 v97, v106, v97
	v_cvt_pk_bf16_f32 v83, v96, v97
	v_mul_f32_e32 v104, v107, v104
	v_mul_f32_e32 v105, v107, v105
	v_cvt_pk_bf16_f32 v87, v104, v105
	global_store_dwordx4 v[4:5], v[80:83], off offset:-1024
	global_store_dwordx4 v[4:5], v[84:87], off
	v_cmp_lt_i32_e32 vcc, s73, v2
	v_lshl_add_u64 v[4:5], v[4:5], 0, s[26:27]
	s_or_b64 s[28:29], vcc, s[28:29]
	s_andn2_b64 exec, exec, s[28:29]
	s_cbranch_execnz .LBB0_229
; __device__ __forceinline__ int ltid() { int t = threadIdx.x; asm volatile("" : "+v"(t)); return t; }
; #define PG8_STAGE(bufoff, gbase, voff) do { _Pragma("unroll") for (int _i = 0; _i < 2; ++_i) \
;         __builtin_amdgcn_global_load_lds((const unsigned*)((const char*)(gbase) + (voff)[_i]), (LAS unsigned*)(lds + (bufoff) + ldsw + _i * 8192), 16, 0, 0); } while (0)
; #define PG8_WAIT_V(n) asm volatile("s_waitcnt vmcnt(" #n ")" ::: "memory")
; #define PG8_BAR __builtin_amdgcn_s_barrier()
; template <class Epi>
; __device__ __forceinline__ void gemm_phase(LAS unsigned char* lds, const Gemm g, const StaticOrder& S, const Epi& E) {
;     const int tid = ltid(), wid = __builtin_amdgcn_readfirstlane(tid >> 6), lane = tid & 63, wr = wid >> 2, wc = wid & 3, fr = lane & 15, fq = lane >> 4;
;     const int K = g.K, nt = K / BK;
;     unsigned voffA[2], voffB[2];
; #pragma unroll
;     for (int i = 0; i < 2; ++i) { int R, C; stage_rc(tid * 16 + i * 8192, R, C); voffA[i] = (unsigned)(R * g.lda + C) * 2u; voffB[i] = (unsigned)(R * g.ldb + C) * 2u; }
;     const size_t kstep = (size_t)(BK * 2);
;     const size_t hstepA = (size_t)HALF * g.lda * 2, hstepB = (size_t)HALF * g.ldb * 2;
;     const size_t tstepA = 2 * hstepA, tstepB = 2 * hstepB;
;     const unsigned ldsw = (unsigned)wid * 1024u;
;     const int aoff = lds_byte(wr * 64 + fr, fq * 8), boff = lds_byte(wc * 32 + fr, fq * 8);
;     ...
;     Unit cur, nxt; int ui = 0;
;     if (!S.next(0, cur)) return;
;     f32x4 acc[2][2][4][2];
; #pragma unroll
;     for (int a = 0; a < 2; ++a)
; #pragma unroll
;         for (int b = 0; b < 2; ++b)
; #pragma unroll
;             for (int m = 0; m < 4; ++m)
; #pragma unroll
;                 for (int n = 0; n < 2; ++n) acc[a][b][m][n] = (f32x4){0.f, 0.f, 0.f, 0.f};
;     bf16x8 At[4][2], B0[2][2], B1[2][2];
;     const char* cA = (const char*)g.A + (size_t)cur.pm * tstepA; const char* cB = (const char*)g.Bt + (size_t)cur.pn * tstepB;
;     PG8_STAGE(PG8_SB(0, 0), cB, voffB); PG8_STAGE(PG8_SA(0, 0), cA, voffA); PG8_STAGE(PG8_SB(0, 1), cB + hstepB, voffB); PG8_STAGE(PG8_SA(0, 1), cA + hstepA, voffA);
;     if (wr == 1) PG8_BAR;
;     PG8_WAIT_V(4); PG8_BAR;
;     PG8_STAGE(PG8_SB(1, 0), cB + kstep, voffB); PG8_STAGE(PG8_SA(1, 0), cA + kstep, voffA); PG8_STAGE(PG8_SB(1, 1), cB + hstepB + kstep, voffB);
.LBB0_230:
	s_waitcnt vmcnt(0)
	s_or_b64 exec, exec, s[18:19]
	s_mov_b32 s0, s68
	v_readlane_b32 s1, v254, 0
	v_mov_b32_e32 v8, v200
	s_cmpk_gt_i32 s1, 0x82f
	v_readfirstlane_b32 s8, v8
	s_cbranch_scc1 .LBB0_242
	v_lshlrev_b32_e32 v1, 4, v8
	v_add_u32_e32 v3, 0x2000, v1
	v_ashrrev_i32_e32 v2, 31, v3
	v_lshrrev_b32_e32 v2, 22, v2
	v_add_u32_e32 v2, v3, v2
	v_ashrrev_i32_e32 v2, 10, v2
	v_lshlrev_b32_e32 v4, 5, v2
	v_and_b32_e32 v5, 32, v4
	v_mul_i32_i24_e32 v4, 0x400, v2
	v_sub_u32_e32 v3, v3, v4
	v_lshrrev_b32_e32 v4, 4, v3
	v_bitop3_b32 v4, v4, v3, 32 bitop3:0x6c
	v_ashrrev_i32_e32 v3, 31, v4
	v_lshrrev_b32_e32 v3, 26, v3
	v_add_u32_e32 v6, v4, v3
	v_ashrrev_i32_e32 v3, 6, v6
	v_and_b32_e32 v6, 0xc0, v6
	v_sub_u32_e32 v4, v4, v6
	v_ashrrev_i16_sdwa v4, v201, sext(v4) dst_sel:DWORD dst_unused:UNUSED_PAD src0_sel:DWORD src1_sel:BYTE_0
	v_lshlrev_b32_e32 v6, 3, v2
	v_readlane_b32 s6, v255, 30
	v_bfe_i32 v4, v4, 0, 16
	v_and_b32_e32 v6, 0x3ffff0, v6
	v_readlane_b32 s7, v255, 31
	v_add_u32_e32 v5, v5, v4
	v_add_lshl_u32 v6, v3, v6, 10
	s_load_dwordx2 s[6:7], s[6:7], 0x118
	v_lshl_add_u32 v130, v5, 1, v6
	v_ashrrev_i32_e32 v5, 31, v8
	v_lshrrev_b32_e32 v5, 26, v5
	v_add_u32_e32 v5, v8, v5
	v_ashrrev_i32_e32 v5, 6, v5
	v_lshlrev_b32_e32 v6, 5, v5
	s_waitcnt lgkmcnt(0)
	s_add_u32 s9, s6, 0xf00000
	v_and_b32_e32 v9, 32, v6
	v_bfe_i32 v6, v8, 27, 1
	s_addc_u32 s10, s7, 0
	v_lshrrev_b32_e32 v6, 22, v6
	s_ashr_i32 s12, s1, 31
	v_add_u32_e32 v6, v1, v6
	s_lshr_b32 s6, s12, 29
	v_and_b32_e32 v6, 0xfffffc00, v6
	s_add_i32 s6, s1, s6
	s_ashr_i32 s17, s8, 6
	v_sub_u32_e32 v1, v1, v6
	s_ashr_i32 s7, s6, 3
	s_and_b32 s6, s6, -8
	s_ashr_i32 s19, s8, 8
	s_lshl_b32 s11, s17, 10
	v_lshrrev_b32_e32 v6, 4, v1
	s_sub_i32 s6, s1, s6
	v_bitop3_b32 v7, v6, v1, 32 bitop3:0x6c
	v_ashrrev_i32_e32 v1, 31, v1
	s_cmp_lt_i32 s6, 0
	s_movk_i32 s13, 0x107
	v_lshrrev_b32_e32 v1, 26, v1
	s_cselect_b32 s13, s13, 0x106
	v_add_u32_e32 v1, v7, v1
	s_mul_i32 s6, s6, s13
	v_ashrrev_i32_e32 v6, 6, v1
	s_add_i32 s6, s6, s7
	v_mul_i32_i24_e32 v1, 64, v6
	s_ashr_i32 s7, s6, 31
	v_sub_u32_e32 v1, v7, v1
	s_lshr_b32 s7, s7, 26
	v_ashrrev_i16_sdwa v1, v201, sext(v1) dst_sel:DWORD dst_unused:UNUSED_PAD src0_sel:DWORD src1_sel:BYTE_0
	s_add_i32 s7, s6, s7
	v_bfe_i32 v7, v1, 0, 16
	s_ashr_i32 s13, s7, 6
	v_add_u32_e32 v1, v9, v7
	v_lshlrev_b32_e32 v9, 3, v5
	s_lshl_b32 s13, s13, 3
	v_and_b32_e32 v9, 0x3ffff0, v9
	s_sub_i32 s14, 0x106, s13
	v_add_lshl_u32 v9, v6, v9, 10
	s_min_u32 s14, s14, 8
	s_andn2_b32 s7, s7, 63
	v_lshl_add_u32 v132, v1, 1, v9
	s_sub_i32 s15, s6, s7
	v_cvt_f32_ubyte0_e32 v9, s14
	v_cvt_f32_i32_e32 v1, s15
	v_rcp_iflag_f32_e32 v10, v9
	s_ashr_i32 s6, s15, 30
	s_or_b32 s16, s6, 1
	v_mul_f32_e32 v10, v1, v10
	v_trunc_f32_e32 v10, v10
	v_fma_f32 v1, -v10, v9, v1
	v_cvt_i32_f32_e32 v10, v10
	v_cmp_ge_f32_e64 s[6:7], |v1|, v9
	s_and_b64 s[6:7], s[6:7], exec
	s_cselect_b32 s6, s16, 0
	v_readfirstlane_b32 s7, v10
	s_add_i32 s18, s7, s6
	s_mul_i32 s6, s18, s14
	s_sub_i32 s6, s15, s6
	s_sext_i32_i8 s6, s6
	s_add_i32 s30, s13, s6
	s_ashr_i32 s31, s30, 31
	s_bfe_i64 s[14:15], s[18:19], 0x80000
	s_lshl_b64 s[6:7], s[30:31], 18
	s_lshl_b64 s[14:15], s[14:15], 18
	s_add_u32 s36, s9, s14
	s_addc_u32 s37, s10, s15
	s_add_i32 s13, s11, 0
	s_add_i32 m0, s13, 0x10000
	v_readlane_b32 s14, v255, 49
	global_load_lds_dwordx4 v132, s[36:37]
	s_add_i32 m0, s13, 0x12000
	v_readlane_b32 s15, v255, 50
	s_add_u32 s34, s14, s6
	global_load_lds_dwordx4 v130, s[36:37]
	s_addc_u32 s35, s15, s7
	s_mov_b32 m0, s13
	s_add_i32 s14, s13, 0x2000
	global_load_lds_dwordx4 v132, s[34:35]
	s_mov_b32 m0, s14
	s_add_u32 s6, s36, 0x20000
	global_load_lds_dwordx4 v130, s[34:35]
	s_addc_u32 s7, s37, 0
	s_add_i32 m0, s13, 0x14000
	s_nop 0
	global_load_lds_dwordx4 v132, s[6:7]
	s_add_i32 m0, s13, 0x16000
	s_nop 0
	global_load_lds_dwordx4 v130, s[6:7]
	s_add_u32 s6, s34, 0x20000
	s_addc_u32 s7, s35, 0
	s_add_i32 s15, s13, 0x4000
	s_mov_b32 m0, s15
	s_add_i32 s16, s13, 0x6000
	global_load_lds_dwordx4 v132, s[6:7]
	s_mov_b32 m0, s16
	s_cmp_lg_u32 s19, 1
	global_load_lds_dwordx4 v130, s[6:7]
	s_cbranch_scc1 .LBB0_233
	s_barrier

; __device__ __forceinline__ float siluf_(float v) { return v * sigmoidf_(v); }
; __device__ __forceinline__ void ssd_item(CPar p, int l, int item, float* sm) {
;     ...
;         if (tid < 384) { const int ch = tid % 192, tlb = (tid / 192) * 32, cc = ch & 63;
;             const float w0 = sW[ch], w1 = sW[192 + ch], w2 = sW[384 + ch], w3 = sW[576 + ch], bias = sW[768 + ch];
;             float r0 = sRaw[(tlb + 0) * 192 + ch], r1 = sRaw[(tlb + 1) * 192 + ch], r2 = sRaw[(tlb + 2) * 192 + ch];
;             float ov[32];
; #pragma unroll
;             for (int i2 = 0; i2 < 32; ++i2) { const float r3 = sRaw[(tlb + i2 + 3) * 192 + ch];
;                 const float v = bias + w0 * r0 + w1 * r1 + w2 * r2 + w3 * r3; ov[i2] = (t0 + tlb + i2 < T) ? siluf_(v) : 0.f; r0 = r1; r1 = r2; r2 = r3; }
.LBB0_455:
	s_or_b64 exec, exec, s[36:37]
	s_waitcnt lgkmcnt(0)
	s_barrier
	s_and_saveexec_b64 s[36:37], s[54:55]
	s_cbranch_execz .LBB0_522
	ds_read2st64_b32 v[30:31], v105 offset1:3
	ds_read2st64_b32 v[28:29], v105 offset0:6 offset1:9
	ds_read_b32 v134, v105 offset:3072
	v_add_u32_e32 v184, 0xd800, v106
	ds_read_b32 v216, v184
	ds_read_b32 v217, v184 offset:768
	ds_read_b32 v218, v184 offset:1536
	ds_read_b32 v219, v184 offset:2304
	ds_read_b32 v220, v184 offset:3072
	ds_read_b32 v221, v184 offset:3840
	ds_read_b32 v222, v184 offset:4608
	ds_read_b32 v223, v184 offset:5376
	ds_read_b32 v224, v184 offset:6144
	ds_read_b32 v225, v184 offset:6912
	ds_read_b32 v226, v184 offset:7680
	ds_read_b32 v227, v184 offset:8448
	ds_read_b32 v228, v184 offset:9216
	ds_read_b32 v229, v184 offset:9984
	ds_read_b32 v230, v184 offset:10752
	ds_read_b32 v231, v184 offset:11520
	ds_read_b32 v232, v184 offset:12288
	ds_read_b32 v233, v184 offset:13056
	ds_read_b32 v234, v184 offset:13824
	ds_read_b32 v235, v184 offset:14592
	ds_read_b32 v236, v184 offset:15360
	ds_read_b32 v237, v184 offset:16128
	ds_read_b32 v238, v184 offset:16896
	ds_read_b32 v239, v184 offset:17664
	ds_read_b32 v240, v184 offset:18432
	ds_read_b32 v241, v184 offset:19200
	ds_read_b32 v242, v184 offset:19968
	ds_read_b32 v243, v184 offset:20736
	ds_read_b32 v244, v184 offset:21504
	ds_read_b32 v245, v184 offset:22272
	ds_read_b32 v246, v184 offset:23040
	ds_read_b32 v247, v184 offset:23808
	ds_read_b32 v248, v184 offset:24576
	ds_read_b32 v249, v184 offset:25344
	ds_read_b32 v250, v184 offset:26112
	v_add_u32_e32 v186, s11, v104
	v_sub_u32_e32 v185, s12, v186
	s_waitcnt lgkmcnt(0)
	v_fma_f32 v176, v30, v216, v134
	v_fma_f32 v177, v30, v217, v134
	v_fma_f32 v178, v30, v218, v134
	v_fma_f32 v179, v30, v219, v134
	v_fmac_f32_e32 v176, v31, v217
	v_fmac_f32_e32 v177, v31, v218
	v_fmac_f32_e32 v178, v31, v219
	v_fmac_f32_e32 v179, v31, v220
	v_fmac_f32_e32 v176, v28, v218
	v_fmac_f32_e32 v177, v28, v219
	v_fmac_f32_e32 v178, v28, v220
	v_fmac_f32_e32 v179, v28, v221
	v_fmac_f32_e32 v176, v29, v219
	v_fmac_f32_e32 v177, v29, v220
	v_fmac_f32_e32 v178, v29, v221
	v_fmac_f32_e32 v179, v29, v222
	v_mul_f32_e32 v180, 0xbfb8aa3b, v176
	v_mul_f32_e32 v181, 0xbfb8aa3b, v177
	v_mul_f32_e32 v182, 0xbfb8aa3b, v178
	v_mul_f32_e32 v183, 0xbfb8aa3b, v179
	v_exp_f32_e32 v180, v180
	v_exp_f32_e32 v181, v181
	v_exp_f32_e32 v182, v182
	v_exp_f32_e32 v183, v183
	v_add_f32_e32 v180, 1.0, v180
	v_add_f32_e32 v181, 1.0, v181
	v_add_f32_e32 v182, 1.0, v182
	v_add_f32_e32 v183, 1.0, v183
	v_rcp_f32_e32 v180, v180
	v_rcp_f32_e32 v181, v181
	v_rcp_f32_e32 v182, v182
	v_rcp_f32_e32 v183, v183
	v_mul_f32_e32 v43, v176, v180
	v_mul_f32_e32 v42, v177, v181
	v_mul_f32_e32 v45, v178, v182
	v_mul_f32_e32 v44, v179, v183
	v_fma_f32 v176, v30, v220, v134
	v_fma_f32 v177, v30, v221, v134
	v_fma_f32 v178, v30, v222, v134
	v_fma_f32 v179, v30, v223, v134
	v_fmac_f32_e32 v176, v31, v221
	v_fmac_f32_e32 v177, v31, v222
	v_fmac_f32_e32 v178, v31, v223
	v_fmac_f32_e32 v179, v31, v224
	v_fmac_f32_e32 v176, v28, v222
	v_fmac_f32_e32 v177, v28, v223
	v_fmac_f32_e32 v178, v28, v224
	v_fmac_f32_e32 v179, v28, v225
	v_fmac_f32_e32 v176, v29, v223
	v_fmac_f32_e32 v177, v29, v224
	v_fmac_f32_e32 v178, v29, v225
	v_fmac_f32_e32 v179, v29, v226
	v_mul_f32_e32 v180, 0xbfb8aa3b, v176
	v_mul_f32_e32 v181, 0xbfb8aa3b, v177
	v_mul_f32_e32 v182, 0xbfb8aa3b, v178
	v_mul_f32_e32 v183, 0xbfb8aa3b, v179
	v_exp_f32_e32 v180, v180
	v_exp_f32_e32 v181, v181
	v_exp_f32_e32 v182, v182
	v_exp_f32_e32 v183, v183
	v_add_f32_e32 v180, 1.0, v180
	v_add_f32_e32 v181, 1.0, v181
	v_add_f32_e32 v182, 1.0, v182
	v_add_f32_e32 v183, 1.0, v183
	v_rcp_f32_e32 v180, v180
	v_rcp_f32_e32 v181, v181
	v_rcp_f32_e32 v182, v182
	v_rcp_f32_e32 v183, v183
	v_mul_f32_e32 v47, v176, v180
	v_mul_f32_e32 v46, v177, v181
	v_mul_f32_e32 v40, v178, v182
	v_mul_f32_e32 v85, v179, v183
	v_fma_f32 v176, v30, v224, v134
	v_fma_f32 v177, v30, v225, v134
	v_fma_f32 v178, v30, v226, v134
	v_fma_f32 v179, v30, v227, v134
	v_fmac_f32_e32 v176, v31, v225
	v_fmac_f32_e32 v177, v31, v226
	v_fmac_f32_e32 v178, v31, v227
	v_fmac_f32_e32 v179, v31, v228
	v_fmac_f32_e32 v176, v28, v226
	v_fmac_f32_e32 v177, v28, v227
	v_fmac_f32_e32 v178, v28, v228
	v_fmac_f32_e32 v179, v28, v229
	v_fmac_f32_e32 v176, v29, v227
	v_fmac_f32_e32 v177, v29, v228
	v_fmac_f32_e32 v178, v29, v229
	v_fmac_f32_e32 v179, v29, v230
	v_mul_f32_e32 v180, 0xbfb8aa3b, v176
	v_mul_f32_e32 v181, 0xbfb8aa3b, v177
	v_mul_f32_e32 v182, 0xbfb8aa3b, v178
	v_mul_f32_e32 v183, 0xbfb8aa3b, v179
	v_exp_f32_e32 v180, v180
	v_exp_f32_e32 v181, v181
	v_exp_f32_e32 v182, v182
	v_exp_f32_e32 v183, v183
	v_add_f32_e32 v180, 1.0, v180
	v_add_f32_e32 v181, 1.0, v181
	v_add_f32_e32 v182, 1.0, v182
	v_add_f32_e32 v183, 1.0, v183
	v_rcp_f32_e32 v180, v180
	v_rcp_f32_e32 v181, v181
	v_rcp_f32_e32 v182, v182
	v_rcp_f32_e32 v183, v183
	v_mul_f32_e32 v87, v176, v180
	v_mul_f32_e32 v41, v177, v181
	v_mul_f32_e32 v91, v178, v182
	v_mul_f32_e32 v89, v179, v183
	v_fma_f32 v176, v30, v228, v134
	v_fma_f32 v177, v30, v229, v134
	v_fma_f32 v178, v30, v230, v134
	v_fma_f32 v179, v30, v231, v134
	v_fmac_f32_e32 v176, v31, v229
	v_fmac_f32_e32 v177, v31, v230
	v_fmac_f32_e32 v178, v31, v231
	v_fmac_f32_e32 v179, v31, v232
	v_fmac_f32_e32 v176, v28, v230
	v_fmac_f32_e32 v177, v28, v231
	v_fmac_f32_e32 v178, v28, v232
	v_fmac_f32_e32 v179, v28, v233
	v_fmac_f32_e32 v176, v29, v231
	v_fmac_f32_e32 v177, v29, v232
	v_fmac_f32_e32 v178, v29, v233
	v_fmac_f32_e32 v179, v29, v234
	v_mul_f32_e32 v180, 0xbfb8aa3b, v176
	v_mul_f32_e32 v181, 0xbfb8aa3b, v177
; __device__ __forceinline__ float siluf_(float v) { return v * sigmoidf_(v); }
; __device__ __forceinline__ void ssd_item(CPar p, int l, int item, float* sm) {
;     ...
;             float ov[32];
; #pragma unroll
;             for (int i2 = 0; i2 < 32; ++i2) { const float r3 = sRaw[(tlb + i2 + 3) * 192 + ch];
;                 const float v = bias + w0 * r0 + w1 * r1 + w2 * r2 + w3 * r3; ov[i2] = (t0 + tlb + i2 < T) ? siluf_(v) : 0.f; r0 = r1; r1 = r2; r2 = r3; }
	v_mul_f32_e32 v182, 0xbfb8aa3b, v178
	v_mul_f32_e32 v183, 0xbfb8aa3b, v179
	v_exp_f32_e32 v180, v180
	v_exp_f32_e32 v181, v181
	v_exp_f32_e32 v182, v182
	v_exp_f32_e32 v183, v183
	v_add_f32_e32 v180, 1.0, v180
	v_add_f32_e32 v181, 1.0, v181
	v_add_f32_e32 v182, 1.0, v182
	v_add_f32_e32 v183, 1.0, v183
	v_rcp_f32_e32 v180, v180
	v_rcp_f32_e32 v181, v181
	v_rcp_f32_e32 v182, v182
	v_rcp_f32_e32 v183, v183
	v_mul_f32_e32 v95, v176, v180
	v_mul_f32_e32 v93, v177, v181
	v_mul_f32_e32 v99, v178, v182
	v_mul_f32_e32 v97, v179, v183
	v_fma_f32 v176, v30, v232, v134
	v_fma_f32 v177, v30, v233, v134
	v_fma_f32 v178, v30, v234, v134
	v_fma_f32 v179, v30, v235, v134
	v_fmac_f32_e32 v176, v31, v233
	v_fmac_f32_e32 v177, v31, v234
	v_fmac_f32_e32 v178, v31, v235
	v_fmac_f32_e32 v179, v31, v236
	v_fmac_f32_e32 v176, v28, v234
	v_fmac_f32_e32 v177, v28, v235
	v_fmac_f32_e32 v178, v28, v236
	v_fmac_f32_e32 v179, v28, v237
	v_fmac_f32_e32 v176, v29, v235
	v_fmac_f32_e32 v177, v29, v236
	v_fmac_f32_e32 v178, v29, v237
	v_fmac_f32_e32 v179, v29, v238
	v_mul_f32_e32 v180, 0xbfb8aa3b, v176
	v_mul_f32_e32 v181, 0xbfb8aa3b, v177
	v_mul_f32_e32 v182, 0xbfb8aa3b, v178
	v_mul_f32_e32 v183, 0xbfb8aa3b, v179
	v_exp_f32_e32 v180, v180
	v_exp_f32_e32 v181, v181
	v_exp_f32_e32 v182, v182
	v_exp_f32_e32 v183, v183
	v_add_f32_e32 v180, 1.0, v180
	v_add_f32_e32 v181, 1.0, v181
	v_add_f32_e32 v182, 1.0, v182
	v_add_f32_e32 v183, 1.0, v183
	v_rcp_f32_e32 v180, v180
	v_rcp_f32_e32 v181, v181
	v_rcp_f32_e32 v182, v182
	v_rcp_f32_e32 v183, v183
	v_mul_f32_e32 v137, v176, v180
	v_mul_f32_e32 v136, v177, v181
	v_mul_f32_e32 v139, v178, v182
	v_mul_f32_e32 v138, v179, v183
	v_fma_f32 v176, v30, v236, v134
	v_fma_f32 v177, v30, v237, v134
	v_fma_f32 v178, v30, v238, v134
	v_fma_f32 v179, v30, v239, v134
	v_fmac_f32_e32 v176, v31, v237
	v_fmac_f32_e32 v177, v31, v238
	v_fmac_f32_e32 v178, v31, v239
	v_fmac_f32_e32 v179, v31, v240
	v_fmac_f32_e32 v176, v28, v238
	v_fmac_f32_e32 v177, v28, v239
	v_fmac_f32_e32 v178, v28, v240
	v_fmac_f32_e32 v179, v28, v241
	v_fmac_f32_e32 v176, v29, v239
	v_fmac_f32_e32 v177, v29, v240
	v_fmac_f32_e32 v178, v29, v241
	v_fmac_f32_e32 v179, v29, v242
	v_mul_f32_e32 v180, 0xbfb8aa3b, v176
	v_mul_f32_e32 v181, 0xbfb8aa3b, v177
	v_mul_f32_e32 v182, 0xbfb8aa3b, v178
	v_mul_f32_e32 v183, 0xbfb8aa3b, v179
	v_exp_f32_e32 v180, v180
	v_exp_f32_e32 v181, v181
	v_exp_f32_e32 v182, v182
	v_exp_f32_e32 v183, v183
	v_add_f32_e32 v180, 1.0, v180
	v_add_f32_e32 v181, 1.0, v181
	v_add_f32_e32 v182, 1.0, v182
	v_add_f32_e32 v183, 1.0, v183
	v_rcp_f32_e32 v180, v180
	v_rcp_f32_e32 v181, v181
	v_rcp_f32_e32 v182, v182
	v_rcp_f32_e32 v183, v183
	v_mul_f32_e32 v141, v176, v180
	v_mul_f32_e32 v140, v177, v181
	v_mul_f32_e32 v143, v178, v182
	v_mul_f32_e32 v142, v179, v183
	v_fma_f32 v176, v30, v240, v134
	v_fma_f32 v177, v30, v241, v134
	v_fma_f32 v178, v30, v242, v134
	v_fma_f32 v179, v30, v243, v134
	v_fmac_f32_e32 v176, v31, v241
	v_fmac_f32_e32 v177, v31, v242
	v_fmac_f32_e32 v178, v31, v243
	v_fmac_f32_e32 v179, v31, v244
	v_fmac_f32_e32 v176, v28, v242
	v_fmac_f32_e32 v177, v28, v243
	v_fmac_f32_e32 v178, v28, v244
	v_fmac_f32_e32 v179, v28, v245
	v_fmac_f32_e32 v176, v29, v243
	v_fmac_f32_e32 v177, v29, v244
	v_fmac_f32_e32 v178, v29, v245
	v_fmac_f32_e32 v179, v29, v246
	v_mul_f32_e32 v180, 0xbfb8aa3b, v176
	v_mul_f32_e32 v181, 0xbfb8aa3b, v177
	v_mul_f32_e32 v182, 0xbfb8aa3b, v178
	v_mul_f32_e32 v183, 0xbfb8aa3b, v179
	v_exp_f32_e32 v180, v180
	v_exp_f32_e32 v181, v181
	v_exp_f32_e32 v182, v182
	v_exp_f32_e32 v183, v183
	v_add_f32_e32 v180, 1.0, v180
	v_add_f32_e32 v181, 1.0, v181
	v_add_f32_e32 v182, 1.0, v182
	v_add_f32_e32 v183, 1.0, v183
	v_rcp_f32_e32 v180, v180
	v_rcp_f32_e32 v181, v181
	v_rcp_f32_e32 v182, v182
	v_rcp_f32_e32 v183, v183
	v_mul_f32_e32 v145, v176, v180
	v_mul_f32_e32 v144, v177, v181
	v_mul_f32_e32 v147, v178, v182
	v_mul_f32_e32 v146, v179, v183
	v_fma_f32 v176, v30, v244, v134
	v_fma_f32 v177, v30, v245, v134
	v_fma_f32 v178, v30, v246, v134
	v_fma_f32 v179, v30, v247, v134
	v_fmac_f32_e32 v176, v31, v245
	v_fmac_f32_e32 v177, v31, v246
	v_fmac_f32_e32 v178, v31, v247
	v_fmac_f32_e32 v179, v31, v248
	v_fmac_f32_e32 v176, v28, v246
	v_fmac_f32_e32 v177, v28, v247
	v_fmac_f32_e32 v178, v28, v248
	v_fmac_f32_e32 v179, v28, v249
	v_fmac_f32_e32 v176, v29, v247
	v_fmac_f32_e32 v177, v29, v248
	v_fmac_f32_e32 v178, v29, v249
	v_fmac_f32_e32 v179, v29, v250
	v_mul_f32_e32 v180, 0xbfb8aa3b, v176
	v_mul_f32_e32 v181, 0xbfb8aa3b, v177
	v_mul_f32_e32 v182, 0xbfb8aa3b, v178
	v_mul_f32_e32 v183, 0xbfb8aa3b, v179
	v_exp_f32_e32 v180, v180
	v_exp_f32_e32 v181, v181
	v_exp_f32_e32 v182, v182
	v_exp_f32_e32 v183, v183
	v_add_f32_e32 v180, 1.0, v180
	v_add_f32_e32 v181, 1.0, v181
	v_add_f32_e32 v182, 1.0, v182
	v_add_f32_e32 v183, 1.0, v183
	v_rcp_f32_e32 v180, v180
	v_rcp_f32_e32 v181, v181
	v_rcp_f32_e32 v182, v182
	v_rcp_f32_e32 v183, v183
	v_mul_f32_e32 v148, v176, v180
	v_mul_f32_e32 v34, v177, v181
	v_mul_f32_e32 v32, v178, v182
	v_mul_f32_e32 v38, v179, v183
	v_cmp_gt_i32_e32 vcc, 32, v185
	s_and_b64 vcc, exec, vcc
	s_cbranch_vccz .Lconv_nomask
; __device__ __forceinline__ float siluf_(float v) { return v * sigmoidf_(v); }
; __device__ __forceinline__ void ssd_item(CPar p, int l, int item, float* sm) {
;     ...
;             for (int i2 = 0; i2 < 32; ++i2) { const float r3 = sRaw[(tlb + i2 + 3) * 192 + ch];
;                 const float v = bias + w0 * r0 + w1 * r1 + w2 * r2 + w3 * r3; ov[i2] = (t0 + tlb + i2 < T) ? siluf_(v) : 0.f; r0 = r1; r1 = r2; r2 = r3; }
	v_cmp_lt_i32_e32 vcc, 0, v185
	s_nop 1
	v_cndmask_b32_e32 v43, 0, v43, vcc
	v_cmp_lt_i32_e32 vcc, 1, v185
	s_nop 1
	v_cndmask_b32_e32 v42, 0, v42, vcc
	v_cmp_lt_i32_e32 vcc, 2, v185
	s_nop 1
	v_cndmask_b32_e32 v45, 0, v45, vcc
	v_cmp_lt_i32_e32 vcc, 3, v185
	s_nop 1
	v_cndmask_b32_e32 v44, 0, v44, vcc
	v_cmp_lt_i32_e32 vcc, 4, v185
	s_nop 1
	v_cndmask_b32_e32 v47, 0, v47, vcc
	v_cmp_lt_i32_e32 vcc, 5, v185
	s_nop 1
	v_cndmask_b32_e32 v46, 0, v46, vcc
	v_cmp_lt_i32_e32 vcc, 6, v185
	s_nop 1
	v_cndmask_b32_e32 v40, 0, v40, vcc
	v_cmp_lt_i32_e32 vcc, 7, v185
	s_nop 1
	v_cndmask_b32_e32 v85, 0, v85, vcc
	v_cmp_lt_i32_e32 vcc, 8, v185
	s_nop 1
	v_cndmask_b32_e32 v87, 0, v87, vcc
	v_cmp_lt_i32_e32 vcc, 9, v185
	s_nop 1
	v_cndmask_b32_e32 v41, 0, v41, vcc
	v_cmp_lt_i32_e32 vcc, 10, v185
	s_nop 1
	v_cndmask_b32_e32 v91, 0, v91, vcc
	v_cmp_lt_i32_e32 vcc, 11, v185
	s_nop 1
	v_cndmask_b32_e32 v89, 0, v89, vcc
	v_cmp_lt_i32_e32 vcc, 12, v185
	s_nop 1
	v_cndmask_b32_e32 v95, 0, v95, vcc
	v_cmp_lt_i32_e32 vcc, 13, v185
	s_nop 1
	v_cndmask_b32_e32 v93, 0, v93, vcc
	v_cmp_lt_i32_e32 vcc, 14, v185
	s_nop 1
	v_cndmask_b32_e32 v99, 0, v99, vcc
	v_cmp_lt_i32_e32 vcc, 15, v185
	s_nop 1
	v_cndmask_b32_e32 v97, 0, v97, vcc
	v_cmp_lt_i32_e32 vcc, 16, v185
	s_nop 1
	v_cndmask_b32_e32 v137, 0, v137, vcc
	v_cmp_lt_i32_e32 vcc, 17, v185
	s_nop 1
	v_cndmask_b32_e32 v136, 0, v136, vcc
	v_cmp_lt_i32_e32 vcc, 18, v185
	s_nop 1
	v_cndmask_b32_e32 v139, 0, v139, vcc
	v_cmp_lt_i32_e32 vcc, 19, v185
	s_nop 1
	v_cndmask_b32_e32 v138, 0, v138, vcc
	v_cmp_lt_i32_e32 vcc, 20, v185
	s_nop 1
	v_cndmask_b32_e32 v141, 0, v141, vcc
	v_cmp_lt_i32_e32 vcc, 21, v185
	s_nop 1
	v_cndmask_b32_e32 v140, 0, v140, vcc
	v_cmp_lt_i32_e32 vcc, 22, v185
	s_nop 1
	v_cndmask_b32_e32 v143, 0, v143, vcc
	v_cmp_lt_i32_e32 vcc, 23, v185
	s_nop 1
	v_cndmask_b32_e32 v142, 0, v142, vcc
	v_cmp_lt_i32_e32 vcc, 24, v185
	s_nop 1
	v_cndmask_b32_e32 v145, 0, v145, vcc
	v_cmp_lt_i32_e32 vcc, 25, v185
	s_nop 1
	v_cndmask_b32_e32 v144, 0, v144, vcc
	v_cmp_lt_i32_e32 vcc, 26, v185
	s_nop 1
	v_cndmask_b32_e32 v147, 0, v147, vcc
	v_cmp_lt_i32_e32 vcc, 27, v185
	s_nop 1
	v_cndmask_b32_e32 v146, 0, v146, vcc
	v_cmp_lt_i32_e32 vcc, 28, v185
	s_nop 1
	v_cndmask_b32_e32 v148, 0, v148, vcc
	v_cmp_lt_i32_e32 vcc, 29, v185
	s_nop 1
	v_cndmask_b32_e32 v34, 0, v34, vcc
	v_cmp_lt_i32_e32 vcc, 30, v185
	s_nop 1
	v_cndmask_b32_e32 v32, 0, v32, vcc
	v_cmp_lt_i32_e32 vcc, 31, v185
	s_nop 1
	v_cndmask_b32_e32 v38, 0, v38, vcc
.Lconv_nomask:
	s_and_saveexec_b64 vcc, s[58:59]
	s_cbranch_execnz .LBB0_559

; __device__ __forceinline__ unsigned pk2(float lo, float hi) { unsigned r; asm volatile("v_cvt_pk_bf16_f32 %0, %1, %2" : "=v"(r) : "v"(lo), "v"(hi)); return r; }
; __device__ __forceinline__ void ssd_item(CPar p, int l, int item, float* sm) {
;     ...
;             if (ch < 128) { bf16_t* dst = (ch < 64 ? XT : WB) + cc * LB + tlb;
; #pragma unroll
;                 for (int q4 = 0; q4 < 4; ++q4) { u32x4 w;
; #pragma unroll
;                     for (int c4 = 0; c4 < 4; ++c4) { const int i2 = q4 * 8 + c4 * 2; const float s0 = ch < 64 ? 1.f : sw[tlb + i2], s1 = ch < 64 ? 1.f : sw[tlb + i2 + 1]; w[c4] = pk2(ov[i2] * s0, ov[i2 + 1] * s1); }
;                     *(u32x4*)(dst + q4 * 8) = w; } }
.LBB0_559:
	v_mov_b32_e32 v216, 1.0
	v_mov_b32_e32 v217, 1.0
	v_mov_b32_e32 v218, 1.0
	v_mov_b32_e32 v219, 1.0
	v_mov_b32_e32 v220, 1.0
	v_mov_b32_e32 v221, 1.0
	v_mov_b32_e32 v222, 1.0
	v_mov_b32_e32 v223, 1.0
	v_mov_b32_e32 v224, 1.0
	v_mov_b32_e32 v225, 1.0
	v_mov_b32_e32 v226, 1.0
	v_mov_b32_e32 v227, 1.0
	v_mov_b32_e32 v228, 1.0
	v_mov_b32_e32 v229, 1.0
	v_mov_b32_e32 v230, 1.0
	v_mov_b32_e32 v231, 1.0
	v_mov_b32_e32 v232, 1.0
	v_mov_b32_e32 v233, 1.0
	v_mov_b32_e32 v234, 1.0
	v_mov_b32_e32 v235, 1.0
	v_mov_b32_e32 v236, 1.0
	v_mov_b32_e32 v237, 1.0
	v_mov_b32_e32 v238, 1.0
	v_mov_b32_e32 v239, 1.0
	v_mov_b32_e32 v240, 1.0
	v_mov_b32_e32 v241, 1.0
	v_mov_b32_e32 v242, 1.0
	v_mov_b32_e32 v243, 1.0
	v_mov_b32_e32 v244, 1.0
	v_mov_b32_e32 v245, 1.0
	v_mov_b32_e32 v246, 1.0
	v_mov_b32_e32 v247, 1.0
	s_and_saveexec_b64 s[96:97], s[56:57]
	ds_read_b32 v216, v108
	ds_read_b32 v217, v108 offset:4
	ds_read_b32 v218, v108 offset:8
	ds_read_b32 v219, v108 offset:12
	ds_read_b32 v220, v108 offset:16
	ds_read_b32 v221, v108 offset:20
	ds_read_b32 v222, v108 offset:24
	ds_read_b32 v223, v108 offset:28
	ds_read_b32 v224, v108 offset:32
	ds_read_b32 v225, v108 offset:36
	ds_read_b32 v226, v108 offset:40
	ds_read_b32 v227, v108 offset:44
	ds_read_b32 v228, v108 offset:48
	ds_read_b32 v229, v108 offset:52
	ds_read_b32 v230, v108 offset:56
	ds_read_b32 v231, v108 offset:60
	ds_read_b32 v232, v108 offset:64
	ds_read_b32 v233, v108 offset:68
	ds_read_b32 v234, v108 offset:72
	ds_read_b32 v235, v108 offset:76
	ds_read_b32 v236, v108 offset:80
	ds_read_b32 v237, v108 offset:84
	ds_read_b32 v238, v108 offset:88
	ds_read_b32 v239, v108 offset:92
	ds_read_b32 v240, v108 offset:96
	ds_read_b32 v241, v108 offset:100
	ds_read_b32 v242, v108 offset:104
	ds_read_b32 v243, v108 offset:108
	ds_read_b32 v244, v108 offset:112
	ds_read_b32 v245, v108 offset:116
	ds_read_b32 v246, v108 offset:120
	ds_read_b32 v247, v108 offset:124
	s_or_b64 exec, exec, s[96:97]
	s_waitcnt lgkmcnt(0)
	v_mul_f32_e32 v29, v43, v216
	v_mul_f32_e32 v28, v42, v217
	v_cvt_pk_bf16_f32 v28, v29, v28
	v_mul_f32_e32 v30, v45, v218
	v_mul_f32_e32 v29, v44, v219
	v_cvt_pk_bf16_f32 v29, v30, v29
	v_mul_f32_e32 v31, v47, v220
	v_mul_f32_e32 v30, v46, v221
	v_cvt_pk_bf16_f32 v30, v31, v30
	v_mul_f32_e32 v31, v85, v223
	v_mul_f32_e32 v33, v40, v222
	v_cvt_pk_bf16_f32 v31, v33, v31
	ds_write_b128 v107, v[28:31]
	v_mul_f32_e32 v29, v87, v224
	v_mul_f32_e32 v28, v41, v225
	v_cvt_pk_bf16_f32 v28, v29, v28
	v_mul_f32_e32 v30, v91, v226
	v_mul_f32_e32 v29, v89, v227
	v_cvt_pk_bf16_f32 v29, v30, v29
	v_mul_f32_e32 v31, v95, v228
	v_mul_f32_e32 v30, v93, v229
	v_cvt_pk_bf16_f32 v30, v31, v30
	v_mul_f32_e32 v31, v97, v231
	v_mul_f32_e32 v33, v99, v230
	v_cvt_pk_bf16_f32 v31, v33, v31
	ds_write_b128 v107, v[28:31] offset:16
	v_mul_f32_e32 v29, v137, v232
	v_mul_f32_e32 v28, v136, v233
	v_cvt_pk_bf16_f32 v28, v29, v28
	v_mul_f32_e32 v30, v139, v234
	v_mul_f32_e32 v29, v138, v235
	v_cvt_pk_bf16_f32 v29, v30, v29
	v_mul_f32_e32 v31, v141, v236
	v_mul_f32_e32 v30, v140, v237
	v_cvt_pk_bf16_f32 v30, v31, v30
	v_mul_f32_e32 v31, v142, v239
	v_mul_f32_e32 v33, v143, v238
	v_cvt_pk_bf16_f32 v31, v33, v31
	ds_write_b128 v107, v[28:31] offset:32
	v_mul_f32_e32 v29, v145, v240
	v_mul_f32_e32 v28, v144, v241
	v_cvt_pk_bf16_f32 v28, v29, v28
	v_mul_f32_e32 v30, v147, v242
	v_mul_f32_e32 v29, v146, v243
	v_cvt_pk_bf16_f32 v29, v30, v29
	v_mul_f32_e32 v31, v148, v244
	v_mul_f32_e32 v30, v34, v245
	v_cvt_pk_bf16_f32 v30, v31, v30
	v_mul_f32_e32 v31, v38, v247
	v_mul_f32_e32 v33, v32, v246
	v_cvt_pk_bf16_f32 v31, v33, v31
	ds_write_b128 v107, v[28:31] offset:48
	s_or_b64 exec, exec, vcc
	s_and_b64 exec, exec, s[56:57]
	s_cbranch_execnz .LBB0_521
	s_branch .LBB0_522

; __device__ __forceinline__ unsigned pk2(float lo, float hi) { unsigned r; asm volatile("v_cvt_pk_bf16_f32 %0, %1, %2" : "=v"(r) : "v"(lo), "v"(hi)); return r; }
; template <int MAP, bool PERMALL = false>
; __device__ __forceinline__ void prep_w(bf16_t* dst, const float* src, int K, int N, int ld, const float* scale, size_t gtid, size_t gsz) {
;     ...
;         float v[8];
; #pragma unroll
;         for (int kk = 0; kk < 8; ++kk) { const int k = k8 * 8 + kk; float x = (c >= 0) ? src[(size_t)k * ld + c] : 0.f; if (scale) x *= scale[k]; v[kk] = x; }
;         u32x4 o; o[0] = pk2(v[0], v[1]); o[1] = pk2(v[2], v[3]); o[2] = pk2(v[4], v[5]); o[3] = pk2(v[6], v[7]);
;         *(u32x4*)(dst + (size_t)n * K + k8 * 8) = o;
.LBB0_818:
	s_and_b64 vcc, exec, s[42:43]
	s_cbranch_vccnz .Lprep_la_noscale
	s_waitcnt vmcnt(0)
	v_mul_f32_e32 v1, v1, v80
	v_mul_f32_e32 v7, v7, v81
	v_mul_f32_e32 v17, v17, v82
	v_mul_f32_e32 v21, v21, v83
	v_mul_f32_e32 v26, v26, v84
	v_mul_f32_e32 v27, v27, v85
	v_mul_f32_e32 v28, v28, v86
	v_mul_f32_e32 v20, v20, v87

; template <int MAP, bool PERMALL = false>
; __device__ __forceinline__ void prep_w(bf16_t* dst, const float* src, int K, int N, int ld, const float* scale, size_t gtid, size_t gsz) {
;     ...
;     for (size_t it = gtid; it < items; it += gsz) {
;         const int n = (int)(it % N), k8 = (int)(it / N);
;         const bool pm_ = PERMALL || MAP == 2 || (MAP == 1 && (n < 2816 || (n >= 4352 && n < 7424)));
;         const int np = pm_ ? (n & ~31) + perm32(n & 31) : n;
;         const int c = MAP == 1 ? col_in(np) : (MAP == 2 ? (((np >> 7) & 1) * 1024 + (np >> 8) * 128 + (np & 127)) : np);
;         float v[8];
; #pragma unroll
;         for (int kk = 0; kk < 8; ++kk) { const int k = k8 * 8 + kk; float x = (c >= 0) ? src[(size_t)k * ld + c] : 0.f; if (scale) x *= scale[k]; v[kk] = x; }
.LBB0_819:
	v_and_b32_e32 v7, 0x3e0, v18
	v_lshlrev_b32_e32 v22, 2, v7
	v_mov_b32_e32 v23, v0
	v_lshl_add_u64 v[22:23], s[44:45], 0, v[22:23]
	v_and_b32_e32 v24, 16, v18
	v_mov_b32_e32 v25, v0
	v_alignbit_b32 v1, v19, v18, 10
	v_and_b32_e32 v21, 24, v14
	v_lshl_add_u64 v[22:23], v[22:23], 0, v[24:25]
	v_mov_b32_e32 v17, v0
	v_lshlrev_b32_e32 v20, 3, v1
	v_lshl_add_u64 v[22:23], v[22:23], 0, v[16:17]
	v_lshlrev_b32_e32 v24, 2, v21
	v_mov_b32_e32 v21, v0
	v_lshl_add_u64 v[22:23], v[22:23], 0, v[24:25]
	v_lshlrev_b64 v[24:25], 12, v[20:21]
	v_lshl_add_u64 v[24:25], v[22:23], 0, v[24:25]
	global_load_dword v1, v[24:25], off
	v_cndmask_b32_e64 v7, 0, 1, s[50:51]
	v_cmp_ne_u32_e64 s[42:43], 1, v7
	s_andn2_b64 vcc, exec, s[50:51]
	v_lshl_add_u64 v[24:25], v[20:21], 2, s[46:47]
	s_cbranch_vccnz .LBB0_821
	global_load_dword v80, v[24:25], off
.LBB0_821:
	v_or_b32_e32 v26, 1, v20
	v_mov_b32_e32 v27, v0
	v_lshlrev_b64 v[26:27], 12, v[26:27]
	v_lshl_add_u64 v[26:27], v[22:23], 0, v[26:27]
	global_load_dword v7, v[26:27], off
	s_and_b64 vcc, exec, s[42:43]
	s_cbranch_vccnz .LBB0_823
	global_load_dword v81, v[24:25], off offset:4
.LBB0_823:
	v_or_b32_e32 v26, 2, v20
	v_mov_b32_e32 v27, v0
	v_lshlrev_b64 v[26:27], 12, v[26:27]
	v_lshl_add_u64 v[26:27], v[22:23], 0, v[26:27]
	global_load_dword v17, v[26:27], off
	s_and_b64 vcc, exec, s[42:43]
	s_cbranch_vccnz .LBB0_825
	global_load_dword v82, v[24:25], off offset:8
.LBB0_825:
	v_or_b32_e32 v26, 3, v20
	v_mov_b32_e32 v27, v0
	v_lshlrev_b64 v[26:27], 12, v[26:27]
	v_lshl_add_u64 v[26:27], v[22:23], 0, v[26:27]
	global_load_dword v21, v[26:27], off
	s_and_b64 vcc, exec, s[42:43]
	s_cbranch_vccnz .LBB0_827
	global_load_dword v83, v[24:25], off offset:12
.LBB0_827:
	v_or_b32_e32 v26, 4, v20
	v_mov_b32_e32 v27, v0
	v_lshlrev_b64 v[26:27], 12, v[26:27]
	v_lshl_add_u64 v[26:27], v[22:23], 0, v[26:27]
	global_load_dword v26, v[26:27], off
	s_and_b64 vcc, exec, s[42:43]
	s_cbranch_vccnz .LBB0_829
	global_load_dword v84, v[24:25], off offset:16
.LBB0_829:
	v_or_b32_e32 v28, 5, v20
	v_mov_b32_e32 v29, v0
	v_lshlrev_b64 v[28:29], 12, v[28:29]
	v_lshl_add_u64 v[28:29], v[22:23], 0, v[28:29]
	global_load_dword v27, v[28:29], off
	s_and_b64 vcc, exec, s[42:43]
	s_cbranch_vccnz .LBB0_831
	global_load_dword v85, v[24:25], off offset:20
.LBB0_831:
	v_or_b32_e32 v28, 6, v20
	v_mov_b32_e32 v29, v0
	v_lshlrev_b64 v[28:29], 12, v[28:29]
	v_lshl_add_u64 v[28:29], v[22:23], 0, v[28:29]
	global_load_dword v28, v[28:29], off
	s_and_b64 vcc, exec, s[42:43]
	s_cbranch_vccnz .LBB0_833
	global_load_dword v86, v[24:25], off offset:24
.LBB0_833:
	v_or_b32_e32 v30, 7, v20
	v_mov_b32_e32 v31, v0
	v_lshlrev_b64 v[30:31], 12, v[30:31]
	v_lshl_add_u64 v[22:23], v[22:23], 0, v[30:31]
	global_load_dword v20, v[22:23], off
	s_and_b64 vcc, exec, s[42:43]
	s_cbranch_vccnz .LBB0_818
	global_load_dword v87, v[24:25], off offset:28
	s_branch .LBB0_818

; __device__ __forceinline__ unsigned pk2(float lo, float hi) { unsigned r; asm volatile("v_cvt_pk_bf16_f32 %0, %1, %2" : "=v"(r) : "v"(lo), "v"(hi)); return r; }
; template <int MAP, bool PERMALL = false>
; __device__ __forceinline__ void prep_w(bf16_t* dst, const float* src, int K, int N, int ld, const float* scale, size_t gtid, size_t gsz) {
;     ...
;         float v[8];
; #pragma unroll
;         for (int kk = 0; kk < 8; ++kk) { const int k = k8 * 8 + kk; float x = (c >= 0) ? src[(size_t)k * ld + c] : 0.f; if (scale) x *= scale[k]; v[kk] = x; }
;         u32x4 o; o[0] = pk2(v[0], v[1]); o[1] = pk2(v[2], v[3]); o[2] = pk2(v[4], v[5]); o[3] = pk2(v[6], v[7]);
;         *(u32x4*)(dst + (size_t)n * K + k8 * 8) = o;
.LBB0_843:
	s_and_b64 vcc, exec, s[40:41]
	s_cbranch_vccnz .Lprep_up_noscale
	s_waitcnt vmcnt(0)
	v_mul_f32_e32 v1, v1, v80
	v_mul_f32_e32 v7, v7, v81
	v_mul_f32_e32 v13, v13, v82
	v_mul_f32_e32 v18, v18, v83
	v_mul_f32_e32 v19, v19, v84
	v_mul_f32_e32 v20, v20, v85
	v_mul_f32_e32 v21, v21, v86
	v_mul_f32_e32 v12, v12, v87

; template <int MAP, bool PERMALL = false>
; __device__ __forceinline__ void prep_w(bf16_t* dst, const float* src, int K, int N, int ld, const float* scale, size_t gtid, size_t gsz) {
;     ...
;     for (size_t it = gtid; it < items; it += gsz) {
;         const int n = (int)(it % N), k8 = (int)(it / N);
;         const bool pm_ = PERMALL || MAP == 2 || (MAP == 1 && (n < 2816 || (n >= 4352 && n < 7424)));
;         const int np = pm_ ? (n & ~31) + perm32(n & 31) : n;
;         const int c = MAP == 1 ? col_in(np) : (MAP == 2 ? (((np >> 7) & 1) * 1024 + (np >> 8) * 128 + (np & 127)) : np);
;         float v[8];
; #pragma unroll
;         for (int kk = 0; kk < 8; ++kk) { const int k = k8 * 8 + kk; float x = (c >= 0) ? src[(size_t)k * ld + c] : 0.f; if (scale) x *= scale[k]; v[kk] = x; }
.LBB0_844:
	v_and_b32_e32 v7, 0xfe0, v10
	v_lshlrev_b32_e32 v14, 2, v7
	v_mov_b32_e32 v15, v0
	v_lshl_add_u64 v[14:15], s[42:43], 0, v[14:15]
	v_and_b32_e32 v16, 16, v10
	v_mov_b32_e32 v17, v0
	v_alignbit_b32 v1, v11, v10, 12
	v_and_b32_e32 v13, 24, v4
	v_lshl_add_u64 v[14:15], v[14:15], 0, v[16:17]
	v_mov_b32_e32 v7, v0
	v_lshlrev_b32_e32 v12, 3, v1
	v_lshl_add_u64 v[14:15], v[14:15], 0, v[6:7]
	v_lshlrev_b32_e32 v16, 2, v13
	v_mov_b32_e32 v13, v0
	v_lshl_add_u64 v[14:15], v[14:15], 0, v[16:17]
	v_lshlrev_b64 v[16:17], 14, v[12:13]
	v_lshl_add_u64 v[16:17], v[14:15], 0, v[16:17]
	global_load_dword v1, v[16:17], off
	v_cndmask_b32_e64 v7, 0, 1, s[48:49]
	v_cmp_ne_u32_e64 s[40:41], 1, v7
	s_andn2_b64 vcc, exec, s[48:49]
	v_lshl_add_u64 v[16:17], v[12:13], 2, s[44:45]
	s_cbranch_vccnz .LBB0_846
	global_load_dword v80, v[16:17], off
.LBB0_846:
	v_or_b32_e32 v18, 1, v12
	v_mov_b32_e32 v19, v0
	v_lshlrev_b64 v[18:19], 14, v[18:19]
	v_lshl_add_u64 v[18:19], v[14:15], 0, v[18:19]
	global_load_dword v7, v[18:19], off
	s_and_b64 vcc, exec, s[40:41]
	s_cbranch_vccnz .LBB0_848
	global_load_dword v81, v[16:17], off offset:4
.LBB0_848:
	v_or_b32_e32 v18, 2, v12
	v_mov_b32_e32 v19, v0
	v_lshlrev_b64 v[18:19], 14, v[18:19]
	v_lshl_add_u64 v[18:19], v[14:15], 0, v[18:19]
	global_load_dword v13, v[18:19], off
	s_and_b64 vcc, exec, s[40:41]
	s_cbranch_vccnz .LBB0_850
	global_load_dword v82, v[16:17], off offset:8
.LBB0_850:
	v_or_b32_e32 v18, 3, v12
	v_mov_b32_e32 v19, v0
	v_lshlrev_b64 v[18:19], 14, v[18:19]
	v_lshl_add_u64 v[18:19], v[14:15], 0, v[18:19]
	global_load_dword v18, v[18:19], off
	s_and_b64 vcc, exec, s[40:41]
	s_cbranch_vccnz .LBB0_852
	global_load_dword v83, v[16:17], off offset:12
.LBB0_852:
	v_or_b32_e32 v20, 4, v12
	v_mov_b32_e32 v21, v0
	v_lshlrev_b64 v[20:21], 14, v[20:21]
	v_lshl_add_u64 v[20:21], v[14:15], 0, v[20:21]
	global_load_dword v19, v[20:21], off
	s_and_b64 vcc, exec, s[40:41]
	s_cbranch_vccnz .LBB0_854
	global_load_dword v84, v[16:17], off offset:16
.LBB0_854:
	v_or_b32_e32 v20, 5, v12
	v_mov_b32_e32 v21, v0
	v_lshlrev_b64 v[20:21], 14, v[20:21]
	v_lshl_add_u64 v[20:21], v[14:15], 0, v[20:21]
	global_load_dword v20, v[20:21], off
	s_and_b64 vcc, exec, s[40:41]
	s_cbranch_vccnz .LBB0_856
	global_load_dword v85, v[16:17], off offset:20
.LBB0_856:
	v_or_b32_e32 v22, 6, v12
	v_mov_b32_e32 v23, v0
	v_lshlrev_b64 v[22:23], 14, v[22:23]
	v_lshl_add_u64 v[22:23], v[14:15], 0, v[22:23]
	global_load_dword v21, v[22:23], off
	s_and_b64 vcc, exec, s[40:41]
	s_cbranch_vccnz .LBB0_858
	global_load_dword v86, v[16:17], off offset:24
.LBB0_858:
	v_or_b32_e32 v22, 7, v12
	v_mov_b32_e32 v23, v0
	v_lshlrev_b64 v[22:23], 14, v[22:23]
	v_lshl_add_u64 v[14:15], v[14:15], 0, v[22:23]
	global_load_dword v12, v[14:15], off
	s_and_b64 vcc, exec, s[40:41]
	s_cbranch_vccnz .LBB0_843
	global_load_dword v87, v[16:17], off offset:28
	s_branch .LBB0_843
